# e49: e44 + barrier waiters poll the top-level arrival counter (>= n_xcd*(k+1)) instead of the generation word the last arriver bumps afterwards
# baseline (speedup 1.0000x reference)
; __device__ __forceinline__ unsigned xb_ld(unsigned* p)              { return __hip_atomic_load(p, __ATOMIC_RELAXED, __HIP_MEMORY_SCOPE_AGENT); }
; #define XB_SPIN(cond, bar) do { unsigned _sp = 0; while (cond) { __builtin_amdgcn_s_sleep(1); \
;     if ((++_sp & 255u) == 0u) { if (xb_ld(&(bar)[XB_TMO])) break; if (_sp > XB_SPIN_CAP) { atomicAdd(&(bar)[XB_TMO], 1u); break; } } } } while (0)
; #define SUB(i, ...) do { if (PROBE_PH == phk && PROBE_SUB == (i)) { __syncthreads(); tp0 = __builtin_amdgcn_s_memrealtime(); } __VA_ARGS__ if (PROBE_PH == phk && PROBE_SUB == (i)) { asm volatile("s_waitcnt vmcnt(0)" ::: "memory"); __syncthreads(); tp1 = __builtin_amdgcn_s_memrealtime(); } } while (0)
; __device__ __forceinline__ void xcd_barrier(const XcdBarrier& b) {
;     ...
;             else XB_SPIN(xb_ld(&bar[XB_TOPGEN]) == tg, bar);
; __global__ void __launch_bounds__(NTHREADS, 2) mk_fwd(Args a) {
;     ...
;         { pg8::ListOrder S; S.init(32, 1, 8, G, vcu >= 128 && vcu < 160 ? vcu - 128 : 1 << 20);
;           EpiWp E{(f16*)(a.ws + WS_WIN)};
;           SUB(3, pg8::gemm_phase<CfgWp, EpiWp, pg8::ListOrder, true, true>(lds, (const char*)(a.ws + WS_WPOOL), (const char*)(a.ws + WS_WRAW), S, E); ); }
;         SUB(1, norm_rows(vcu * NWAVES + wave, lane, a.in[0], a.in[2], a.in[6], (const float*)(a.ws + WS_MOD), (f16*)(a.ws + WS_H)); );
.LBB0_165:
	s_and_saveexec_b64 s[2:3], s[82:83]
	s_cbranch_execz .Lp1_waited
	v_mov_b32_e32 v2, 0x3400
	s_mov_b32 s0, 0
	v_mov_b32_e32 v3, 0x23004
	ds_read_b32 v3, v3
	s_waitcnt lgkmcnt(0)
	v_readfirstlane_b32 s101, v3
.Lp1_wait:
	global_load_dword v3, v2, s[50:51] sc1
	s_add_u32 s0, s0, 1
	s_waitcnt vmcnt(0)
	v_readfirstlane_b32 s1, v3
	s_cmp_ge_u32 s1, s101
	s_cbranch_scc1 .Lp1_polled
	s_cmp_gt_u32 s0, 0x4000
	s_cbranch_scc1 .Lp1_polled
	s_sleep 1
	s_branch .Lp1_wait

; __device__ __forceinline__ unsigned xb_ld(unsigned* p)              { return __hip_atomic_load(p, __ATOMIC_RELAXED, __HIP_MEMORY_SCOPE_AGENT); }
; __device__ __forceinline__ unsigned xb_add(unsigned* p, unsigned v) { return __hip_atomic_fetch_add(p, v, __ATOMIC_RELAXED, __HIP_MEMORY_SCOPE_AGENT); }
; #define XB_SPIN(cond, bar) do { unsigned _sp = 0; while (cond) { __builtin_amdgcn_s_sleep(1); \
;     if ((++_sp & 255u) == 0u) { if (xb_ld(&(bar)[XB_TMO])) break; if (_sp > XB_SPIN_CAP) { atomicAdd(&(bar)[XB_TMO], 1u); break; } } } } while (0)
; __device__ __forceinline__ void xcd_barrier(const XcdBarrier& b) {
;     ...
;         const unsigned old = xb_add(&bar[XB_XSUB(b.x)], 1u);
;         const unsigned gen = old / nloc;
;         if (old + 1u == (gen + 1u) * nloc) {
;             __builtin_amdgcn_fence(__ATOMIC_RELEASE, "agent");
;             asm volatile("s_waitcnt vmcnt(0)" ::: "memory");
;             const unsigned og = xb_add(&bar[XB_TOP], 1u);
;             const unsigned tg = og / nx;
;             if (og + 1u == (tg + 1u) * nx) xb_add(&bar[XB_TOPGEN], 1u);
;             else XB_SPIN(xb_ld(&bar[XB_TOPGEN]) == tg, bar);
;             __builtin_amdgcn_fence(__ATOMIC_ACQUIRE, "agent");
;             xb_add(&bar[XB_XGEN(b.x)], 1u);
;             asm volatile("s_waitcnt vmcnt(0)" ::: "memory");
;         } else {
;             XB_SPIN(xb_ld(&bar[XB_XGEN(b.x)]) == gen, bar);
.LBB0_249:
	s_or_b64 exec, exec, s[10:11]
	v_cvt_f32_u32_e32 v5, v3
	s_waitcnt vmcnt(0)
	v_readfirstlane_b32 s0, v4
	v_sub_u32_e32 v4, 0, v3
	v_rcp_iflag_f32_e32 v5, v5
	v_add_u32_e32 v6, s0, v2
	v_mul_f32_e32 v5, 0x4f7ffffe, v5
	v_cvt_u32_f32_e32 v5, v5
	v_mul_lo_u32 v2, v4, v5
	v_mul_hi_u32 v2, v5, v2
	v_add_u32_e32 v2, v5, v2
	v_mul_hi_u32 v2, v6, v2
	v_mul_lo_u32 v4, v2, v3
	v_sub_u32_e32 v4, v6, v4
	v_add_u32_e32 v5, 1, v2
	v_cmp_ge_u32_e32 vcc, v4, v3
	s_nop 1
	v_cndmask_b32_e32 v2, v2, v5, vcc
	v_sub_u32_e32 v5, v4, v3
	v_cndmask_b32_e32 v4, v4, v5, vcc
	v_add_u32_e32 v5, 1, v2
	v_cmp_ge_u32_e32 vcc, v4, v3
	v_add_u32_e32 v4, 1, v6
	s_nop 0
	v_cndmask_b32_e32 v2, v2, v5, vcc
	v_mul_lo_u32 v5, v3, v2
	v_add_u32_e32 v3, v5, v3
	v_cmp_ne_u32_e32 vcc, v4, v3
	s_and_saveexec_b64 s[0:1], vcc
	s_xor_b64 s[8:9], exec, s[0:1]
	s_cbranch_execz .LBB0_263
	s_waitcnt lgkmcnt(0)
	buffer_inv sc1
	v_mul_u32_u24_e32 v2, 2, v1
	v_mov_b32_e32 v1, 0x3400
	global_load_dword v1, v1, s[50:51] sc1
	s_add_u32 s12, s50, 0x3400
	s_addc_u32 s13, s51, 0
	s_waitcnt vmcnt(0)
	v_cmp_lt_u32_e32 vcc, v1, v2
	s_and_saveexec_b64 s[10:11], vcc
	s_cbranch_execz .LBB0_262
	s_mov_b32 s0, 1
	s_mov_b64 s[14:15], 0
	v_mov_b32_e32 v1, 0
	s_branch .LBB0_253

; __device__ __forceinline__ unsigned xb_ld(unsigned* p)              { return __hip_atomic_load(p, __ATOMIC_RELAXED, __HIP_MEMORY_SCOPE_AGENT); }
; #define XB_SPIN(cond, bar) do { unsigned _sp = 0; while (cond) { __builtin_amdgcn_s_sleep(1); \
;     if ((++_sp & 255u) == 0u) { if (xb_ld(&(bar)[XB_TMO])) break; if (_sp > XB_SPIN_CAP) { atomicAdd(&(bar)[XB_TMO], 1u); break; } } } } while (0)
; __device__ __forceinline__ void xcd_barrier(const XcdBarrier& b) {
;     ...
;             else XB_SPIN(xb_ld(&bar[XB_TOPGEN]) == tg, bar);
.LBB0_257:
	global_load_dword v3, v1, s[12:13] sc1
	s_add_i32 s0, s0, 1
	s_mov_b64 s[24:25], -1
	s_waitcnt vmcnt(0)
	v_cmp_ge_u32_e32 vcc, v3, v2
	s_orn2_b64 s[22:23], vcc, exec
	s_branch .LBB0_252

; __device__ __forceinline__ unsigned xb_ld(unsigned* p)              { return __hip_atomic_load(p, __ATOMIC_RELAXED, __HIP_MEMORY_SCOPE_AGENT); }
; __device__ __forceinline__ unsigned xb_add(unsigned* p, unsigned v) { return __hip_atomic_fetch_add(p, v, __ATOMIC_RELAXED, __HIP_MEMORY_SCOPE_AGENT); }
; #define XB_SPIN(cond, bar) do { unsigned _sp = 0; while (cond) { __builtin_amdgcn_s_sleep(1); \
;     if ((++_sp & 255u) == 0u) { if (xb_ld(&(bar)[XB_TMO])) break; if (_sp > XB_SPIN_CAP) { atomicAdd(&(bar)[XB_TMO], 1u); break; } } } } while (0)
; __device__ __forceinline__ void xcd_barrier(const XcdBarrier& b) {
;     ...
;             const unsigned og = xb_add(&bar[XB_TOP], 1u);
;             const unsigned tg = og / nx;
;             if (og + 1u == (tg + 1u) * nx) xb_add(&bar[XB_TOPGEN], 1u);
;             else XB_SPIN(xb_ld(&bar[XB_TOPGEN]) == tg, bar);
.LBB0_266:
	s_or_b64 exec, exec, s[10:11]
	v_cvt_f32_u32_e32 v4, v1
	s_waitcnt vmcnt(0)
	v_readfirstlane_b32 s0, v3
	s_add_u32 s10, s50, 0x3500
	s_addc_u32 s11, s51, 0
	v_rcp_iflag_f32_e32 v4, v4
	v_add_u32_e32 v2, s0, v2
	v_add_u32_e32 v5, 1, v2
	s_mov_b64 s[12:13], -1
	v_mul_f32_e32 v3, 0x4f7ffffe, v4
	v_cvt_u32_f32_e32 v3, v3
	v_sub_u32_e32 v4, 0, v1
	v_mul_lo_u32 v4, v4, v3
	v_mul_hi_u32 v4, v3, v4
	v_add_u32_e32 v3, v3, v4
	v_mul_hi_u32 v3, v2, v3
	v_mul_lo_u32 v4, v3, v1
	v_sub_u32_e32 v2, v2, v4
	v_add_u32_e32 v6, 1, v3
	v_cmp_ge_u32_e32 vcc, v2, v1
	v_sub_u32_e32 v4, v2, v1
	s_nop 0
	v_cndmask_b32_e32 v3, v3, v6, vcc
	v_cndmask_b32_e32 v2, v2, v4, vcc
	v_add_u32_e32 v4, 1, v3
	v_cmp_ge_u32_e32 vcc, v2, v1
	s_nop 1
	v_cndmask_b32_e32 v4, v3, v4, vcc
	v_mul_lo_u32 v2, v1, v4
	v_add_u32_e32 v1, v2, v1
	v_cmp_ne_u32_e32 vcc, v5, v1
	v_mov_b64_e32 v[2:3], s[10:11]
	s_and_saveexec_b64 s[8:9], vcc
	s_cbranch_execz .LBB0_278
	v_mov_b32_e32 v4, v1
	v_mov_b32_e32 v1, 0
	global_load_dword v2, v1, s[10:11] offset:-256 sc1
	s_mov_b64 s[20:21], 0
	s_waitcnt vmcnt(0)
	v_cmp_lt_u32_e32 vcc, v2, v4
	s_and_saveexec_b64 s[14:15], vcc
	s_cbranch_execz .LBB0_277
	s_add_u32 s12, s50, 0x200
	s_addc_u32 s13, s51, 0
	s_mov_b32 s0, 1
	s_branch .LBB0_270

; __device__ __forceinline__ unsigned xb_ld(unsigned* p)              { return __hip_atomic_load(p, __ATOMIC_RELAXED, __HIP_MEMORY_SCOPE_AGENT); }
; #define XB_SPIN(cond, bar) do { unsigned _sp = 0; while (cond) { __builtin_amdgcn_s_sleep(1); \
;     if ((++_sp & 255u) == 0u) { if (xb_ld(&(bar)[XB_TMO])) break; if (_sp > XB_SPIN_CAP) { atomicAdd(&(bar)[XB_TMO], 1u); break; } } } } while (0)
; __device__ __forceinline__ void xcd_barrier(const XcdBarrier& b) {
;     ...
;             else XB_SPIN(xb_ld(&bar[XB_TOPGEN]) == tg, bar);
.LBB0_274:
	global_load_dword v2, v1, s[10:11] offset:-256 sc1
	s_add_i32 s0, s0, 1
	s_mov_b64 s[24:25], -1
	s_waitcnt vmcnt(0)
	v_cmp_ge_u32_e32 vcc, v2, v4
	s_orn2_b64 s[28:29], vcc, exec
	s_branch .LBB0_269

; __device__ __forceinline__ unsigned xb_ld(unsigned* p)              { return __hip_atomic_load(p, __ATOMIC_RELAXED, __HIP_MEMORY_SCOPE_AGENT); }
; __device__ __forceinline__ unsigned xb_add(unsigned* p, unsigned v) { return __hip_atomic_fetch_add(p, v, __ATOMIC_RELAXED, __HIP_MEMORY_SCOPE_AGENT); }
; #define XB_SPIN(cond, bar) do { unsigned _sp = 0; while (cond) { __builtin_amdgcn_s_sleep(1); \
;     if ((++_sp & 255u) == 0u) { if (xb_ld(&(bar)[XB_TMO])) break; if (_sp > XB_SPIN_CAP) { atomicAdd(&(bar)[XB_TMO], 1u); break; } } } } while (0)
; __device__ __forceinline__ void xcd_barrier(const XcdBarrier& b) {
;     ...
;         const unsigned old = xb_add(&bar[XB_XSUB(b.x)], 1u);
;         const unsigned gen = old / nloc;
;         if (old + 1u == (gen + 1u) * nloc) {
;             __builtin_amdgcn_fence(__ATOMIC_RELEASE, "agent");
;             asm volatile("s_waitcnt vmcnt(0)" ::: "memory");
;             const unsigned og = xb_add(&bar[XB_TOP], 1u);
;             const unsigned tg = og / nx;
;             if (og + 1u == (tg + 1u) * nx) xb_add(&bar[XB_TOPGEN], 1u);
;             else XB_SPIN(xb_ld(&bar[XB_TOPGEN]) == tg, bar);
;             __builtin_amdgcn_fence(__ATOMIC_ACQUIRE, "agent");
;             xb_add(&bar[XB_XGEN(b.x)], 1u);
;             asm volatile("s_waitcnt vmcnt(0)" ::: "memory");
;         } else {
;             XB_SPIN(xb_ld(&bar[XB_XGEN(b.x)]) == gen, bar);
.LBB0_455:
	s_or_b64 exec, exec, s[10:11]
	v_cvt_f32_u32_e32 v5, v3
	s_waitcnt vmcnt(0)
	v_readfirstlane_b32 s0, v4
	v_sub_u32_e32 v4, 0, v3
	v_rcp_iflag_f32_e32 v5, v5
	v_add_u32_e32 v6, s0, v2
	v_mul_f32_e32 v5, 0x4f7ffffe, v5
	v_cvt_u32_f32_e32 v5, v5
	v_mul_lo_u32 v2, v4, v5
	v_mul_hi_u32 v2, v5, v2
	v_add_u32_e32 v2, v5, v2
	v_mul_hi_u32 v2, v6, v2
	v_mul_lo_u32 v4, v2, v3
	v_sub_u32_e32 v4, v6, v4
	v_add_u32_e32 v5, 1, v2
	v_cmp_ge_u32_e32 vcc, v4, v3
	s_nop 1
	v_cndmask_b32_e32 v2, v2, v5, vcc
	v_sub_u32_e32 v5, v4, v3
	v_cndmask_b32_e32 v4, v4, v5, vcc
	v_add_u32_e32 v5, 1, v2
	v_cmp_ge_u32_e32 vcc, v4, v3
	v_add_u32_e32 v4, 1, v6
	s_nop 0
	v_cndmask_b32_e32 v2, v2, v5, vcc
	v_mul_lo_u32 v5, v3, v2
	v_add_u32_e32 v3, v5, v3
	v_cmp_ne_u32_e32 vcc, v4, v3
	s_and_saveexec_b64 s[0:1], vcc
	s_xor_b64 s[8:9], exec, s[0:1]
	s_cbranch_execz .LBB0_469
	s_waitcnt lgkmcnt(0)
	buffer_inv sc1
	v_mul_u32_u24_e32 v2, 3, v1
	v_mov_b32_e32 v1, 0x3400
	global_load_dword v1, v1, s[50:51] sc1
	s_add_u32 s12, s50, 0x3400
	s_addc_u32 s13, s51, 0
	s_waitcnt vmcnt(0)
	v_cmp_lt_u32_e32 vcc, v1, v2
	s_and_saveexec_b64 s[10:11], vcc
	s_cbranch_execz .LBB0_468
	s_mov_b32 s0, 1
	s_mov_b64 s[14:15], 0
	v_mov_b32_e32 v1, 0
	s_branch .LBB0_459

; __device__ __forceinline__ unsigned xb_ld(unsigned* p)              { return __hip_atomic_load(p, __ATOMIC_RELAXED, __HIP_MEMORY_SCOPE_AGENT); }
; __device__ __forceinline__ unsigned xb_add(unsigned* p, unsigned v) { return __hip_atomic_fetch_add(p, v, __ATOMIC_RELAXED, __HIP_MEMORY_SCOPE_AGENT); }
; #define XB_SPIN(cond, bar) do { unsigned _sp = 0; while (cond) { __builtin_amdgcn_s_sleep(1); \
;     if ((++_sp & 255u) == 0u) { if (xb_ld(&(bar)[XB_TMO])) break; if (_sp > XB_SPIN_CAP) { atomicAdd(&(bar)[XB_TMO], 1u); break; } } } } while (0)
; __device__ __forceinline__ void xcd_barrier(const XcdBarrier& b) {
;     ...
;         const unsigned old = xb_add(&bar[XB_XSUB(b.x)], 1u);
;         const unsigned gen = old / nloc;
;         if (old + 1u == (gen + 1u) * nloc) {
;             __builtin_amdgcn_fence(__ATOMIC_RELEASE, "agent");
;             asm volatile("s_waitcnt vmcnt(0)" ::: "memory");
;             const unsigned og = xb_add(&bar[XB_TOP], 1u);
;             const unsigned tg = og / nx;
;             if (og + 1u == (tg + 1u) * nx) xb_add(&bar[XB_TOPGEN], 1u);
;             else XB_SPIN(xb_ld(&bar[XB_TOPGEN]) == tg, bar);
;             __builtin_amdgcn_fence(__ATOMIC_ACQUIRE, "agent");
;             xb_add(&bar[XB_XGEN(b.x)], 1u);
;             asm volatile("s_waitcnt vmcnt(0)" ::: "memory");
;         } else {
;             XB_SPIN(xb_ld(&bar[XB_XGEN(b.x)]) == gen, bar);
.LBB0_1016:
	s_or_b64 exec, exec, s[8:9]
	v_cvt_f32_u32_e32 v5, v3
	s_waitcnt vmcnt(0)
	v_readfirstlane_b32 s0, v4
	v_sub_u32_e32 v4, 0, v3
	v_rcp_iflag_f32_e32 v5, v5
	v_add_u32_e32 v6, s0, v2
	v_mul_f32_e32 v5, 0x4f7ffffe, v5
	v_cvt_u32_f32_e32 v5, v5
	v_mul_lo_u32 v2, v4, v5
	v_mul_hi_u32 v2, v5, v2
	v_add_u32_e32 v2, v5, v2
	v_mul_hi_u32 v2, v6, v2
	v_mul_lo_u32 v4, v2, v3
	v_sub_u32_e32 v4, v6, v4
	v_add_u32_e32 v5, 1, v2
	v_cmp_ge_u32_e32 vcc, v4, v3
	s_nop 1
	v_cndmask_b32_e32 v2, v2, v5, vcc
	v_sub_u32_e32 v5, v4, v3
	v_cndmask_b32_e32 v4, v4, v5, vcc
	v_add_u32_e32 v5, 1, v2
	v_cmp_ge_u32_e32 vcc, v4, v3
	v_add_u32_e32 v4, 1, v6
	s_nop 0
	v_cndmask_b32_e32 v2, v2, v5, vcc
	v_mul_lo_u32 v5, v3, v2
	v_add_u32_e32 v3, v5, v3
	v_cmp_ne_u32_e32 vcc, v4, v3
	s_and_saveexec_b64 s[0:1], vcc
	s_xor_b64 s[6:7], exec, s[0:1]
	s_cbranch_execz .LBB0_1030
	s_waitcnt lgkmcnt(0)
	buffer_inv sc1
	v_mul_u32_u24_e32 v2, 4, v1
	v_mov_b32_e32 v1, 0x3400
	global_load_dword v1, v1, s[50:51] sc1
	s_add_u32 s10, s50, 0x3400
	s_addc_u32 s11, s51, 0
	s_waitcnt vmcnt(0)
	v_cmp_lt_u32_e32 vcc, v1, v2
	s_and_saveexec_b64 s[8:9], vcc
	s_cbranch_execz .LBB0_1029
	s_mov_b32 s0, 1
	s_mov_b64 s[12:13], 0
	v_mov_b32_e32 v1, 0
	s_branch .LBB0_1020

; __device__ __forceinline__ unsigned xb_ld(unsigned* p)              { return __hip_atomic_load(p, __ATOMIC_RELAXED, __HIP_MEMORY_SCOPE_AGENT); }
; #define XB_SPIN(cond, bar) do { unsigned _sp = 0; while (cond) { __builtin_amdgcn_s_sleep(1); \
;     if ((++_sp & 255u) == 0u) { if (xb_ld(&(bar)[XB_TMO])) break; if (_sp > XB_SPIN_CAP) { atomicAdd(&(bar)[XB_TMO], 1u); break; } } } } while (0)
; __device__ __forceinline__ void xcd_barrier(const XcdBarrier& b) {
;     ...
;             else XB_SPIN(xb_ld(&bar[XB_TOPGEN]) == tg, bar);
.LBB0_1024:
	global_load_dword v3, v1, s[10:11] sc1
	s_add_i32 s0, s0, 1
	s_mov_b64 s[22:23], -1
	s_waitcnt vmcnt(0)
	v_cmp_ge_u32_e32 vcc, v3, v2
	s_orn2_b64 s[20:21], vcc, exec
	s_branch .LBB0_1019

; __device__ __forceinline__ unsigned xb_ld(unsigned* p)              { return __hip_atomic_load(p, __ATOMIC_RELAXED, __HIP_MEMORY_SCOPE_AGENT); }
; __device__ __forceinline__ unsigned xb_add(unsigned* p, unsigned v) { return __hip_atomic_fetch_add(p, v, __ATOMIC_RELAXED, __HIP_MEMORY_SCOPE_AGENT); }
; #define XB_SPIN(cond, bar) do { unsigned _sp = 0; while (cond) { __builtin_amdgcn_s_sleep(1); \
;     if ((++_sp & 255u) == 0u) { if (xb_ld(&(bar)[XB_TMO])) break; if (_sp > XB_SPIN_CAP) { atomicAdd(&(bar)[XB_TMO], 1u); break; } } } } while (0)
; __device__ __forceinline__ void xcd_barrier(const XcdBarrier& b) {
;     ...
;             const unsigned og = xb_add(&bar[XB_TOP], 1u);
;             const unsigned tg = og / nx;
;             if (og + 1u == (tg + 1u) * nx) xb_add(&bar[XB_TOPGEN], 1u);
;             else XB_SPIN(xb_ld(&bar[XB_TOPGEN]) == tg, bar);
.LBB0_1033:
	s_or_b64 exec, exec, s[8:9]
	v_cvt_f32_u32_e32 v4, v1
	s_waitcnt vmcnt(0)
	v_readfirstlane_b32 s0, v3
	s_add_u32 s8, s50, 0x3500
	s_addc_u32 s9, s51, 0
	v_rcp_iflag_f32_e32 v4, v4
	v_add_u32_e32 v2, s0, v2
	v_add_u32_e32 v5, 1, v2
	s_mov_b64 s[10:11], -1
	v_mul_f32_e32 v3, 0x4f7ffffe, v4
	v_cvt_u32_f32_e32 v3, v3
	v_sub_u32_e32 v4, 0, v1
	v_mul_lo_u32 v4, v4, v3
	v_mul_hi_u32 v4, v3, v4
	v_add_u32_e32 v3, v3, v4
	v_mul_hi_u32 v3, v2, v3
	v_mul_lo_u32 v4, v3, v1
	v_sub_u32_e32 v2, v2, v4
	v_add_u32_e32 v6, 1, v3
	v_cmp_ge_u32_e32 vcc, v2, v1
	v_sub_u32_e32 v4, v2, v1
	s_nop 0
	v_cndmask_b32_e32 v3, v3, v6, vcc
	v_cndmask_b32_e32 v2, v2, v4, vcc
	v_add_u32_e32 v4, 1, v3
	v_cmp_ge_u32_e32 vcc, v2, v1
	s_nop 1
	v_cndmask_b32_e32 v4, v3, v4, vcc
	v_mul_lo_u32 v2, v1, v4
	v_add_u32_e32 v1, v2, v1
	v_cmp_ne_u32_e32 vcc, v5, v1
	v_mov_b64_e32 v[2:3], s[8:9]
	s_and_saveexec_b64 s[6:7], vcc
	s_cbranch_execz .LBB0_1045
	v_mov_b32_e32 v4, v1
	v_mov_b32_e32 v1, 0
	global_load_dword v2, v1, s[8:9] offset:-256 sc1
	s_mov_b64 s[14:15], 0
	s_waitcnt vmcnt(0)
	v_cmp_lt_u32_e32 vcc, v2, v4
	s_and_saveexec_b64 s[12:13], vcc
	s_cbranch_execz .LBB0_1044
	s_add_u32 s10, s50, 0x200
	s_addc_u32 s11, s51, 0
	s_mov_b32 s0, 1
	s_branch .LBB0_1037

; __device__ __forceinline__ unsigned xb_ld(unsigned* p)              { return __hip_atomic_load(p, __ATOMIC_RELAXED, __HIP_MEMORY_SCOPE_AGENT); }
; #define XB_SPIN(cond, bar) do { unsigned _sp = 0; while (cond) { __builtin_amdgcn_s_sleep(1); \
;     if ((++_sp & 255u) == 0u) { if (xb_ld(&(bar)[XB_TMO])) break; if (_sp > XB_SPIN_CAP) { atomicAdd(&(bar)[XB_TMO], 1u); break; } } } } while (0)
; __device__ __forceinline__ void xcd_barrier(const XcdBarrier& b) {
;     ...
;             else XB_SPIN(xb_ld(&bar[XB_TOPGEN]) == tg, bar);
.LBB0_1041:
	global_load_dword v2, v1, s[8:9] offset:-256 sc1
	s_add_i32 s0, s0, 1
	s_mov_b64 s[22:23], -1
	s_waitcnt vmcnt(0)
	v_cmp_ge_u32_e32 vcc, v2, v4
	s_orn2_b64 s[26:27], vcc, exec
	s_branch .LBB0_1036

; __device__ __forceinline__ unsigned xb_ld(unsigned* p)              { return __hip_atomic_load(p, __ATOMIC_RELAXED, __HIP_MEMORY_SCOPE_AGENT); }
; __device__ __forceinline__ unsigned xb_add(unsigned* p, unsigned v) { return __hip_atomic_fetch_add(p, v, __ATOMIC_RELAXED, __HIP_MEMORY_SCOPE_AGENT); }
; #define XB_SPIN(cond, bar) do { unsigned _sp = 0; while (cond) { __builtin_amdgcn_s_sleep(1); \
;     if ((++_sp & 255u) == 0u) { if (xb_ld(&(bar)[XB_TMO])) break; if (_sp > XB_SPIN_CAP) { atomicAdd(&(bar)[XB_TMO], 1u); break; } } } } while (0)
; __device__ __forceinline__ void xcd_barrier(const XcdBarrier& b) {
;     ...
;         const unsigned old = xb_add(&bar[XB_XSUB(b.x)], 1u);
;         const unsigned gen = old / nloc;
;         if (old + 1u == (gen + 1u) * nloc) {
;             __builtin_amdgcn_fence(__ATOMIC_RELEASE, "agent");
;             asm volatile("s_waitcnt vmcnt(0)" ::: "memory");
;             const unsigned og = xb_add(&bar[XB_TOP], 1u);
;             const unsigned tg = og / nx;
;             if (og + 1u == (tg + 1u) * nx) xb_add(&bar[XB_TOPGEN], 1u);
;             else XB_SPIN(xb_ld(&bar[XB_TOPGEN]) == tg, bar);
;             __builtin_amdgcn_fence(__ATOMIC_ACQUIRE, "agent");
;             xb_add(&bar[XB_XGEN(b.x)], 1u);
;             asm volatile("s_waitcnt vmcnt(0)" ::: "memory");
;         } else {
;             XB_SPIN(xb_ld(&bar[XB_XGEN(b.x)]) == gen, bar);
.LBB0_1096:
	s_or_b64 exec, exec, s[10:11]
	v_cvt_f32_u32_e32 v5, v3
	s_waitcnt vmcnt(0)
	v_readfirstlane_b32 s0, v4
	v_sub_u32_e32 v4, 0, v3
	v_rcp_iflag_f32_e32 v5, v5
	v_add_u32_e32 v6, s0, v2
	v_mul_f32_e32 v5, 0x4f7ffffe, v5
	v_cvt_u32_f32_e32 v5, v5
	v_mul_lo_u32 v2, v4, v5
	v_mul_hi_u32 v2, v5, v2
	v_add_u32_e32 v2, v5, v2
	v_mul_hi_u32 v2, v6, v2
	v_mul_lo_u32 v4, v2, v3
	v_sub_u32_e32 v4, v6, v4
	v_add_u32_e32 v5, 1, v2
	v_cmp_ge_u32_e32 vcc, v4, v3
	s_nop 1
	v_cndmask_b32_e32 v2, v2, v5, vcc
	v_sub_u32_e32 v5, v4, v3
	v_cndmask_b32_e32 v4, v4, v5, vcc
	v_add_u32_e32 v5, 1, v2
	v_cmp_ge_u32_e32 vcc, v4, v3
	v_add_u32_e32 v4, 1, v6
	s_nop 0
	v_cndmask_b32_e32 v2, v2, v5, vcc
	v_mul_lo_u32 v5, v3, v2
	v_add_u32_e32 v3, v5, v3
	v_cmp_ne_u32_e32 vcc, v4, v3
	s_and_saveexec_b64 s[0:1], vcc
	s_xor_b64 s[8:9], exec, s[0:1]
	s_cbranch_execz .LBB0_1110
	s_waitcnt lgkmcnt(0)
	buffer_inv sc1
	v_mul_u32_u24_e32 v2, 5, v1
	v_mov_b32_e32 v1, 0x3400
	global_load_dword v1, v1, s[50:51] sc1
	s_add_u32 s12, s50, 0x3400
	s_addc_u32 s13, s51, 0
	s_waitcnt vmcnt(0)
	v_cmp_lt_u32_e32 vcc, v1, v2
	s_and_saveexec_b64 s[10:11], vcc
	s_cbranch_execz .LBB0_1109
	s_mov_b32 s0, 1
	s_mov_b64 s[14:15], 0
	v_mov_b32_e32 v1, 0
	s_branch .LBB0_1100
